# seams 5,12: the per-group L2 write-back is issued by wave 0 right after the DN K-loop (runs beside the epilogue) instead of inside the seam
# baseline (speedup 1.0000x reference)
.LBB0_1039:
	s_add_u32 s98, s40, 0xfff00000
	s_addc_u32 s99, s41, -1
	s_mov_b32 m0, s58
	s_nop 0
	global_load_lds_dwordx4 v138, s[98:99]
	v_add_u32_e32 v154, s62, v156
	ds_read_b128 v[130:133], v154
	ds_read_b128 v[150:153], v154 offset:1024
	ds_read_b128 v[160:163], v154 offset:2048
	ds_read_b128 v[164:167], v154 offset:3072
	v_add_u32_e32 v154, s63, v156
	ds_read_b128 v[168:171], v154
	ds_read_b128 v[172:175], v154 offset:1024
	ds_read_b128 v[180:183], v154 offset:2048
	ds_read_b128 v[184:187], v154 offset:3072
	s_add_u32 s42, s40, 0xfff00080
	s_addc_u32 s43, s41, -1
	s_cmp_eq_u32 s68, 60
	s_cselect_b32 s45, s31, s43
	s_cselect_b32 s44, s39, s42
	s_cselect_b32 s43, s29, s67
	s_cselect_b32 s42, s65, s66
	v_lshl_add_u64 v[154:155], s[40:41], 0, v[144:145]
	s_add_i32 m0, s51, 0xc000
	ds_read_b128 v[188:191], v158
	ds_read_b128 v[192:195], v158 offset:1024
	ds_read_b128 v[196:199], v158 offset:2048
	ds_read_b128 v[200:203], v158 offset:3072
	ds_read_b128 v[204:207], v158 offset:4096
	ds_read_b128 v[208:211], v158 offset:5120
	ds_read_b128 v[212:215], v158 offset:6144
	ds_read_b128 v[216:219], v158 offset:7168
	global_load_lds_dwordx4 v[154:155], off
	v_lshl_add_u64 v[154:155], s[40:41], 0, v[142:143]
	s_add_i32 m0, s51, 0xe000
	s_nop 0
	global_load_lds_dwordx4 v[154:155], off
	s_waitcnt vmcnt(8)
	s_waitcnt lgkmcnt(0)
	v_mfma_f32_16x16x32_bf16 v[114:117], v[130:133], v[188:191], v[114:117]
	v_mfma_f32_16x16x32_bf16 v[118:121], v[160:163], v[188:191], v[118:121]
	v_mfma_f32_16x16x32_bf16 v[98:101], v[130:133], v[196:199], v[98:101]
	v_mfma_f32_16x16x32_bf16 v[102:105], v[160:163], v[196:199], v[102:105]
	s_barrier
	s_setprio 1
	v_mfma_f32_16x16x32_bf16 v[82:85], v[130:133], v[204:207], v[82:85]
	v_mfma_f32_16x16x32_bf16 v[86:89], v[160:163], v[204:207], v[86:89]
	v_mfma_f32_16x16x32_bf16 v[66:69], v[130:133], v[212:215], v[66:69]
	v_mfma_f32_16x16x32_bf16 v[70:73], v[160:163], v[212:215], v[70:73]
	v_mfma_f32_16x16x32_bf16 v[114:117], v[150:153], v[192:195], v[114:117]
	v_mfma_f32_16x16x32_bf16 v[118:121], v[164:167], v[192:195], v[118:121]
	v_mfma_f32_16x16x32_bf16 v[98:101], v[150:153], v[200:203], v[98:101]
	v_mfma_f32_16x16x32_bf16 v[102:105], v[164:167], v[200:203], v[102:105]
	v_mfma_f32_16x16x32_bf16 v[82:85], v[150:153], v[208:211], v[82:85]
	v_mfma_f32_16x16x32_bf16 v[86:89], v[164:167], v[208:211], v[86:89]
	v_mfma_f32_16x16x32_bf16 v[66:69], v[150:153], v[216:219], v[66:69]
	v_mfma_f32_16x16x32_bf16 v[70:73], v[164:167], v[216:219], v[70:73]
	v_mfma_f32_16x16x32_bf16 v[122:125], v[168:171], v[188:191], v[122:125]
	v_mfma_f32_16x16x32_bf16 v[126:129], v[180:183], v[188:191], v[126:129]
	v_mfma_f32_16x16x32_bf16 v[106:109], v[168:171], v[196:199], v[106:109]
	v_mfma_f32_16x16x32_bf16 v[110:113], v[180:183], v[196:199], v[110:113]
	v_mfma_f32_16x16x32_bf16 v[90:93], v[168:171], v[204:207], v[90:93]
	v_mfma_f32_16x16x32_bf16 v[94:97], v[180:183], v[204:207], v[94:97]
	v_mfma_f32_16x16x32_bf16 v[74:77], v[168:171], v[212:215], v[74:77]
	v_mfma_f32_16x16x32_bf16 v[78:81], v[180:183], v[212:215], v[78:81]
	v_mfma_f32_16x16x32_bf16 v[122:125], v[172:175], v[192:195], v[122:125]
	v_mfma_f32_16x16x32_bf16 v[126:129], v[184:187], v[192:195], v[126:129]
	v_mfma_f32_16x16x32_bf16 v[106:109], v[172:175], v[200:203], v[106:109]
	v_mfma_f32_16x16x32_bf16 v[110:113], v[184:187], v[200:203], v[110:113]
	v_mfma_f32_16x16x32_bf16 v[90:93], v[172:175], v[208:211], v[90:93]
	v_mfma_f32_16x16x32_bf16 v[94:97], v[184:187], v[208:211], v[94:97]
	v_mfma_f32_16x16x32_bf16 v[74:77], v[172:175], v[216:219], v[74:77]
	v_mfma_f32_16x16x32_bf16 v[78:81], v[184:187], v[216:219], v[78:81]
	s_setprio 0
	s_barrier
	s_add_i32 s69, s62, s50
	v_lshl_add_u64 v[154:155], s[42:43], 0, v[136:137]
	s_mov_b32 m0, s69
	ds_read_b128 v[188:191], v158 offset:16384
	ds_read_b128 v[192:195], v158 offset:17408
	ds_read_b128 v[196:199], v158 offset:18432
	ds_read_b128 v[200:203], v158 offset:19456
	ds_read_b128 v[204:207], v158 offset:20480
	ds_read_b128 v[208:211], v158 offset:21504
	ds_read_b128 v[212:215], v158 offset:22528
	ds_read_b128 v[216:219], v158 offset:23552
	global_load_lds_dwordx4 v[154:155], off
	s_add_i32 m0, s69, 0x2000
	s_add_u32 s70, s42, 0x100000
	v_lshl_add_u64 v[176:177], s[42:43], 0, v[140:141]
	s_addc_u32 s71, s43, 0
	s_add_i32 s69, s63, s50
	global_load_lds_dwordx4 v[176:177], off
	v_lshl_add_u64 v[220:221], s[70:71], 0, v[136:137]
	s_mov_b32 m0, s69
	v_lshl_add_u64 v[222:223], s[44:45], 0, v[138:139]
	global_load_lds_dwordx4 v[220:221], off
	v_lshl_add_u64 v[220:221], s[70:71], 0, v[140:141]
	s_add_i32 m0, s69, 0x2000
	s_nop 0
	global_load_lds_dwordx4 v[220:221], off
	v_lshl_add_u64 v[220:221], s[44:45], 0, v[134:135]
	s_mov_b32 m0, s51
	s_nop 0
	global_load_lds_dwordx4 v[220:221], off
	s_waitcnt vmcnt(7)
	s_waitcnt lgkmcnt(0)
	v_mfma_f32_16x16x32_bf16 v[50:53], v[130:133], v[188:191], v[50:53]
	v_mfma_f32_16x16x32_bf16 v[54:57], v[160:163], v[188:191], v[54:57]
	v_mfma_f32_16x16x32_bf16 v[26:29], v[130:133], v[196:199], v[26:29]
	v_mfma_f32_16x16x32_bf16 v[30:33], v[160:163], v[196:199], v[30:33]
	s_barrier
	s_setprio 1
	v_mfma_f32_16x16x32_bf16 v[18:21], v[130:133], v[204:207], v[18:21]
	v_mfma_f32_16x16x32_bf16 v[22:25], v[160:163], v[204:207], v[22:25]
	v_mfma_f32_16x16x32_bf16 v[2:5], v[130:133], v[212:215], v[2:5]
	v_mfma_f32_16x16x32_bf16 v[6:9], v[160:163], v[212:215], v[6:9]
	v_mfma_f32_16x16x32_bf16 v[50:53], v[150:153], v[192:195], v[50:53]
	v_mfma_f32_16x16x32_bf16 v[54:57], v[164:167], v[192:195], v[54:57]
	v_mfma_f32_16x16x32_bf16 v[26:29], v[150:153], v[200:203], v[26:29]
	v_mfma_f32_16x16x32_bf16 v[30:33], v[164:167], v[200:203], v[30:33]
	v_mfma_f32_16x16x32_bf16 v[18:21], v[150:153], v[208:211], v[18:21]
	v_mfma_f32_16x16x32_bf16 v[22:25], v[164:167], v[208:211], v[22:25]
	v_mfma_f32_16x16x32_bf16 v[2:5], v[150:153], v[216:219], v[2:5]
	v_mfma_f32_16x16x32_bf16 v[6:9], v[164:167], v[216:219], v[6:9]
	v_mfma_f32_16x16x32_bf16 v[58:61], v[168:171], v[188:191], v[58:61]
	v_mfma_f32_16x16x32_bf16 v[62:65], v[180:183], v[188:191], v[62:65]
	v_mfma_f32_16x16x32_bf16 v[42:45], v[168:171], v[196:199], v[42:45]
	v_mfma_f32_16x16x32_bf16 v[46:49], v[180:183], v[196:199], v[46:49]
	v_mfma_f32_16x16x32_bf16 v[34:37], v[168:171], v[204:207], v[34:37]
	v_mfma_f32_16x16x32_bf16 v[38:41], v[180:183], v[204:207], v[38:41]
	v_mfma_f32_16x16x32_bf16 v[10:13], v[168:171], v[212:215], v[10:13]
	v_mfma_f32_16x16x32_bf16 v[14:17], v[180:183], v[212:215], v[14:17]
	v_mfma_f32_16x16x32_bf16 v[58:61], v[172:175], v[192:195], v[58:61]
	v_mfma_f32_16x16x32_bf16 v[62:65], v[184:187], v[192:195], v[62:65]
	v_mfma_f32_16x16x32_bf16 v[42:45], v[172:175], v[200:203], v[42:45]
	v_mfma_f32_16x16x32_bf16 v[46:49], v[184:187], v[200:203], v[46:49]
	v_mfma_f32_16x16x32_bf16 v[34:37], v[172:175], v[208:211], v[34:37]
	v_mfma_f32_16x16x32_bf16 v[38:41], v[184:187], v[208:211], v[38:41]
	v_mfma_f32_16x16x32_bf16 v[10:13], v[172:175], v[216:219], v[10:13]
	v_mfma_f32_16x16x32_bf16 v[14:17], v[184:187], v[216:219], v[14:17]
	s_setprio 0
	s_barrier
	s_mov_b32 m0, s52
	s_nop 0
	global_load_lds_dwordx4 v138, s[44:45]
	s_add_i32 s69, 0, 0x18000
	s_add_i32 s70, 0, 0x1c000
	v_add_u32_e32 v164, s69, v156
	v_add_u32_e32 v179, s70, v156
	ds_read_b128 v[130:133], v164
	ds_read_b128 v[150:153], v164 offset:1024
	ds_read_b128 v[160:163], v164 offset:2048
	ds_read_b128 v[164:167], v164 offset:3072
	ds_read_b128 v[168:171], v179
	ds_read_b128 v[172:175], v179 offset:1024
	ds_read_b128 v[180:183], v179 offset:2048
	ds_read_b128 v[184:187], v179 offset:3072
	s_add_u32 s44, s44, 0x100000
	s_addc_u32 s45, s45, 0
	s_mov_b32 m0, s53
	v_lshl_add_u64 v[224:225], s[44:45], 0, v[134:135]
	ds_read_b128 v[188:191], v158 offset:32768
	ds_read_b128 v[192:195], v158 offset:33792
	ds_read_b128 v[196:199], v158 offset:34816
	ds_read_b128 v[200:203], v158 offset:35840
	ds_read_b128 v[204:207], v158 offset:36864
	ds_read_b128 v[208:211], v158 offset:37888
	ds_read_b128 v[212:215], v158 offset:38912
	ds_read_b128 v[216:219], v158 offset:39936
	global_load_lds_dwordx4 v[224:225], off
	v_lshl_add_u64 v[224:225], s[44:45], 0, v[138:139]
	s_mov_b32 m0, s54
	s_nop 0
	global_load_lds_dwordx4 v[224:225], off
	s_waitcnt vmcnt(8)
	s_waitcnt lgkmcnt(0)
	v_mfma_f32_16x16x32_bf16 v[114:117], v[130:133], v[188:191], v[114:117]
	v_mfma_f32_16x16x32_bf16 v[118:121], v[160:163], v[188:191], v[118:121]
	v_mfma_f32_16x16x32_bf16 v[98:101], v[130:133], v[196:199], v[98:101]
	v_mfma_f32_16x16x32_bf16 v[102:105], v[160:163], v[196:199], v[102:105]
	s_barrier
	s_setprio 1
	v_mfma_f32_16x16x32_bf16 v[82:85], v[130:133], v[204:207], v[82:85]
	v_mfma_f32_16x16x32_bf16 v[86:89], v[160:163], v[204:207], v[86:89]
	v_mfma_f32_16x16x32_bf16 v[66:69], v[130:133], v[212:215], v[66:69]
	v_mfma_f32_16x16x32_bf16 v[70:73], v[160:163], v[212:215], v[70:73]
	v_mfma_f32_16x16x32_bf16 v[114:117], v[150:153], v[192:195], v[114:117]
	v_mfma_f32_16x16x32_bf16 v[118:121], v[164:167], v[192:195], v[118:121]
	v_mfma_f32_16x16x32_bf16 v[98:101], v[150:153], v[200:203], v[98:101]
	v_mfma_f32_16x16x32_bf16 v[102:105], v[164:167], v[200:203], v[102:105]
	v_mfma_f32_16x16x32_bf16 v[82:85], v[150:153], v[208:211], v[82:85]
	v_mfma_f32_16x16x32_bf16 v[86:89], v[164:167], v[208:211], v[86:89]
	v_mfma_f32_16x16x32_bf16 v[66:69], v[150:153], v[216:219], v[66:69]
	v_mfma_f32_16x16x32_bf16 v[70:73], v[164:167], v[216:219], v[70:73]
	v_mfma_f32_16x16x32_bf16 v[122:125], v[168:171], v[188:191], v[122:125]
	v_mfma_f32_16x16x32_bf16 v[126:129], v[180:183], v[188:191], v[126:129]
	v_mfma_f32_16x16x32_bf16 v[106:109], v[168:171], v[196:199], v[106:109]
	v_mfma_f32_16x16x32_bf16 v[110:113], v[180:183], v[196:199], v[110:113]
	v_mfma_f32_16x16x32_bf16 v[90:93], v[168:171], v[204:207], v[90:93]
	v_mfma_f32_16x16x32_bf16 v[94:97], v[180:183], v[204:207], v[94:97]
	v_mfma_f32_16x16x32_bf16 v[74:77], v[168:171], v[212:215], v[74:77]
	v_mfma_f32_16x16x32_bf16 v[78:81], v[180:183], v[212:215], v[78:81]
	v_mfma_f32_16x16x32_bf16 v[122:125], v[172:175], v[192:195], v[122:125]
	v_mfma_f32_16x16x32_bf16 v[126:129], v[184:187], v[192:195], v[126:129]
	v_mfma_f32_16x16x32_bf16 v[106:109], v[172:175], v[200:203], v[106:109]
	v_mfma_f32_16x16x32_bf16 v[110:113], v[184:187], v[200:203], v[110:113]
	v_mfma_f32_16x16x32_bf16 v[90:93], v[172:175], v[208:211], v[90:93]
	v_mfma_f32_16x16x32_bf16 v[94:97], v[184:187], v[208:211], v[94:97]
	v_mfma_f32_16x16x32_bf16 v[74:77], v[172:175], v[216:219], v[74:77]
	v_mfma_f32_16x16x32_bf16 v[78:81], v[184:187], v[216:219], v[78:81]
	s_setprio 0
	s_barrier
	s_add_i32 s44, s69, s50
	v_lshl_add_u64 v[154:155], v[154:155], 0, s[22:23]
	s_mov_b32 m0, s44
	ds_read_b128 v[188:191], v158 offset:49152
	ds_read_b128 v[192:195], v158 offset:50176
	ds_read_b128 v[196:199], v158 offset:51200
	ds_read_b128 v[200:203], v158 offset:52224
	ds_read_b128 v[204:207], v158 offset:53248
	ds_read_b128 v[208:211], v158 offset:54272
	ds_read_b128 v[212:215], v158 offset:55296
	ds_read_b128 v[216:219], v158 offset:56320
	global_load_lds_dwordx4 v[154:155], off
	s_add_i32 m0, s44, 0x2000
	s_add_u32 s42, s42, 0x100080
	v_lshl_add_u64 v[154:155], v[176:177], 0, s[22:23]
	s_addc_u32 s43, s43, 0
	s_add_i32 s44, s70, s50
	global_load_lds_dwordx4 v[154:155], off
	v_lshl_add_u64 v[154:155], s[42:43], 0, v[136:137]
	s_mov_b32 m0, s44
	s_nop 0
	global_load_lds_dwordx4 v[154:155], off
	v_lshl_add_u64 v[154:155], s[42:43], 0, v[140:141]
	s_add_i32 m0, s44, 0x2000
	s_nop 0
	global_load_lds_dwordx4 v[154:155], off
	v_lshl_add_u64 v[154:155], v[220:221], 0, s[22:23]
	s_mov_b32 m0, s57
	s_nop 0
	global_load_lds_dwordx4 v[154:155], off
	s_waitcnt vmcnt(7)
	s_waitcnt lgkmcnt(0)
	v_mfma_f32_16x16x32_bf16 v[50:53], v[130:133], v[188:191], v[50:53]
	v_mfma_f32_16x16x32_bf16 v[54:57], v[160:163], v[188:191], v[54:57]
	v_mfma_f32_16x16x32_bf16 v[26:29], v[130:133], v[196:199], v[26:29]
	v_mfma_f32_16x16x32_bf16 v[30:33], v[160:163], v[196:199], v[30:33]
	s_barrier
	s_setprio 1
	v_mfma_f32_16x16x32_bf16 v[18:21], v[130:133], v[204:207], v[18:21]
	v_mfma_f32_16x16x32_bf16 v[22:25], v[160:163], v[204:207], v[22:25]
	v_mfma_f32_16x16x32_bf16 v[2:5], v[130:133], v[212:215], v[2:5]
	v_mfma_f32_16x16x32_bf16 v[6:9], v[160:163], v[212:215], v[6:9]
	v_mfma_f32_16x16x32_bf16 v[50:53], v[150:153], v[192:195], v[50:53]
	v_mfma_f32_16x16x32_bf16 v[54:57], v[164:167], v[192:195], v[54:57]
	v_mfma_f32_16x16x32_bf16 v[26:29], v[150:153], v[200:203], v[26:29]
	v_mfma_f32_16x16x32_bf16 v[30:33], v[164:167], v[200:203], v[30:33]
	v_mfma_f32_16x16x32_bf16 v[18:21], v[150:153], v[208:211], v[18:21]
	v_mfma_f32_16x16x32_bf16 v[22:25], v[164:167], v[208:211], v[22:25]
	v_mfma_f32_16x16x32_bf16 v[2:5], v[150:153], v[216:219], v[2:5]
	v_mfma_f32_16x16x32_bf16 v[6:9], v[164:167], v[216:219], v[6:9]
	v_mfma_f32_16x16x32_bf16 v[58:61], v[168:171], v[188:191], v[58:61]
	v_mfma_f32_16x16x32_bf16 v[62:65], v[180:183], v[188:191], v[62:65]
	v_mfma_f32_16x16x32_bf16 v[42:45], v[168:171], v[196:199], v[42:45]
	v_mfma_f32_16x16x32_bf16 v[46:49], v[180:183], v[196:199], v[46:49]
	v_mfma_f32_16x16x32_bf16 v[34:37], v[168:171], v[204:207], v[34:37]
	v_mfma_f32_16x16x32_bf16 v[38:41], v[180:183], v[204:207], v[38:41]
	v_mfma_f32_16x16x32_bf16 v[10:13], v[168:171], v[212:215], v[10:13]
	v_mfma_f32_16x16x32_bf16 v[14:17], v[180:183], v[212:215], v[14:17]
	v_mfma_f32_16x16x32_bf16 v[58:61], v[172:175], v[192:195], v[58:61]
	v_mfma_f32_16x16x32_bf16 v[62:65], v[184:187], v[192:195], v[62:65]
	v_mfma_f32_16x16x32_bf16 v[42:45], v[172:175], v[200:203], v[42:45]
	v_mfma_f32_16x16x32_bf16 v[46:49], v[184:187], v[200:203], v[46:49]
	v_mfma_f32_16x16x32_bf16 v[34:37], v[172:175], v[208:211], v[34:37]
	v_mfma_f32_16x16x32_bf16 v[38:41], v[184:187], v[208:211], v[38:41]
	v_mfma_f32_16x16x32_bf16 v[10:13], v[172:175], v[216:219], v[10:13]
	v_mfma_f32_16x16x32_bf16 v[14:17], v[184:187], v[216:219], v[14:17]
	s_setprio 0
	s_barrier
	s_add_i32 s68, s68, 2
	s_add_u32 s66, s66, 0x100
	s_addc_u32 s67, s67, 0
	s_add_u32 s40, s40, 0x100
	s_addc_u32 s41, s41, 0
	s_cmp_gt_u32 s68, 61
	s_cbranch_scc0 .LBB0_1039
	v_readfirstlane_b32 s98, v178
	s_cmp_lt_u32 s98, 64
	s_cbranch_scc0 .Lkf_5
	v_readlane_b32 s98, v250, 0
	s_cmp_lg_u32 s98, 0
	s_cselect_b32 s98, 1, 0
	s_lshr_b32 s99, s81, 6
	s_cmp_lg_u32 s99, 0
	s_cselect_b32 s99, 1, 0
	s_and_b32 s98, s98, s99
	s_cbranch_scc1 .Lkf_5
	buffer_wbl2 sc1
.Lkf_5:
	s_and_b64 vcc, exec, s[24:25]
	s_cbranch_vccz .LBB0_1042
	s_barrier

.LBB0_1128:
	s_andn2_b64 vcc, exec, s[0:1]
	s_cbranch_vccnz .LBB0_1195
	v_readlane_b32 s0, v249, 4
	v_readlane_b32 s1, v249, 5
	s_cmpk_lt_u32 s1, 0x3e9
	s_mov_b64 s[0:1], -1
	s_cbranch_scc0 .LBB0_1183
	v_readlane_b32 s2, v249, 2
	s_cmpk_eq_i32 s2, 0x100
	s_cbranch_scc0 .Lg5_xcd
	s_waitcnt vmcnt(0)
	s_waitcnt vmcnt(0) lgkmcnt(0)
	s_barrier
	s_mov_b64 s[0:1], exec
	v_readlane_b32 s2, v249, 10
	v_readlane_b32 s3, v249, 11
	s_and_b64 s[2:3], s[0:1], s[2:3]
	s_mov_b64 exec, s[2:3]
	s_cbranch_execz .Lg5_BB0_1004
	s_lshl_b32 s2, s81, 8
	s_and_b32 s2, s2, 0x3f00
	s_mov_b64 s[4:5], exec
	s_add_u32 s2, s82, s2
	s_addc_u32 s3, s83, 0
.Lg5_skip_wbl2_2:
	s_waitcnt vmcnt(0)
	v_mbcnt_lo_u32_b32 v1, s4, 0
	s_add_u32 s2, s2, 0x10000
	v_mbcnt_hi_u32_b32 v2, s5, v1
	s_addc_u32 s3, s3, 0
	v_cmp_eq_u32_e32 vcc, 0, v2
	s_and_saveexec_b64 s[6:7], vcc
	s_cbranch_execz .Lg5_BB0_991
	s_bcnt1_i32_b64 s4, s[4:5]
	v_mov_b32_e32 v1, 0
	v_mov_b32_e32 v3, s4
	global_atomic_add v3, v1, v3, s[2:3] sc0

.LBB0_2264:
	s_andn2_b64 vcc, exec, s[0:1]
	s_cbranch_vccnz .LBB0_2331
	v_readlane_b32 s0, v249, 4
	v_readlane_b32 s1, v249, 5
	s_cmpk_lt_u32 s1, 0x3e9
	s_mov_b64 s[0:1], -1
	s_cbranch_scc0 .LBB0_2319
	v_readlane_b32 s2, v249, 2
	s_cmpk_eq_i32 s2, 0x100
	s_cbranch_scc0 .Lg12_xcd
	s_waitcnt vmcnt(0)
	s_waitcnt vmcnt(0) lgkmcnt(0)
	s_barrier
	s_mov_b64 s[0:1], exec
	v_readlane_b32 s2, v249, 10
	v_readlane_b32 s3, v249, 11
	s_and_b64 s[2:3], s[0:1], s[2:3]
	s_mov_b64 exec, s[2:3]
	s_cbranch_execz .Lg12_BB0_1004
	s_lshl_b32 s2, s81, 8
	s_and_b32 s2, s2, 0x3f00
	s_mov_b64 s[4:5], exec
	s_add_u32 s2, s82, s2
	s_addc_u32 s3, s83, 0
.Lg12_skip_wbl2_2:
	s_waitcnt vmcnt(0)
	v_mbcnt_lo_u32_b32 v1, s4, 0
	s_add_u32 s2, s2, 0x10000
	v_mbcnt_hi_u32_b32 v2, s5, v1
	s_addc_u32 s3, s3, 0
	v_cmp_eq_u32_e32 vcc, 0, v2
	s_and_saveexec_b64 s[6:7], vcc
	s_cbranch_execz .Lg12_BB0_991
	s_bcnt1_i32_b64 s4, s[4:5]
	v_mov_b32_e32 v1, 0
	v_mov_b32_e32 v3, s4
	global_atomic_add v3, v1, v3, s[2:3] sc0
